# v94 with SGPR-base + 32-bit offset addressing on the vT stores (v_mad_u32_u24 instead of 64-bit mad)
# baseline (speedup 1.0000x reference)
.LBB0_431:
	s_andn2_b64 vcc, exec, s[4:5]
	s_cbranch_vccnz .LBB0_391
	v_or_b32_e32 v0, s7, v199
	s_lshl_b32 s7, s35, 8
	s_cmp_lt_u32 s35, 30
	s_mov_b64 s[4:5], -1
	v_ashrrev_i32_e32 v1, 31, v0
	s_cbranch_scc1 .LBB0_434
	s_waitcnt lgkmcnt(0)
	v_readlane_b32 s4, v252, 15
	v_readlane_b32 s5, v252, 16
	v_and_b32_e32 v2, 3, v220
	v_and_b32_e32 v0, 0xffffffe0, v0
	v_lshl_or_b32 v0, v2, 3, v0
	v_ashrrev_i32_e32 v1, 31, v0
	v_add_u32_e32 v10, s7, v200
	v_and_b32_e32 v8, 15, v220
	v_sub_u32_e32 v10, v10, v8
	v_bfe_u32 v8, v220, 2, 4
	v_add_u32_e32 v10, v10, v8
	v_lshl_or_b32 v9, v2, 4, v8
	v_lshlrev_b32_e32 v9, 2, v9
	v_lshlrev_b64 v[6:7], 1, v[0:1]
	v_mov_b64_e32 v[2:3], s[4:5]
	v_mad_u32_u24 v4, v10, s94, v6
	v_cvt_pk_f16_f32 v158, v158, v159
	v_cvt_pk_f16_f32 v159, v160, v161
	v_cvt_pk_f16_f32 v160, v142, v143
	v_cvt_pk_f16_f32 v161, v144, v145
	v_cvt_pk_f16_f32 v94, v94, v95
	v_cvt_pk_f16_f32 v95, v96, v97
	v_cvt_pk_f16_f32 v96, v78, v79
	v_cvt_pk_f16_f32 v97, v80, v81
	v_permlane32_swap_b32_e32 v158, v160
	v_permlane32_swap_b32_e32 v159, v161
	v_permlane32_swap_b32_e32 v94, v96
	v_permlane32_swap_b32_e32 v95, v97
	v_permlane16_swap_b32_e32 v158, v160
	v_permlane16_swap_b32_e32 v159, v161
	v_permlane16_swap_b32_e32 v94, v96
	v_permlane16_swap_b32_e32 v95, v97
	s_nop 1
	ds_bpermute_b32 v158, v9, v158
	ds_bpermute_b32 v159, v9, v159
	ds_bpermute_b32 v160, v9, v160
	ds_bpermute_b32 v161, v9, v161
	ds_bpermute_b32 v94, v9, v94
	ds_bpermute_b32 v95, v9, v95
	ds_bpermute_b32 v96, v9, v96
	ds_bpermute_b32 v97, v9, v97
	s_waitcnt lgkmcnt(0)
	global_store_dwordx4 v4, v[158:161], s[4:5]
	global_store_dwordx4 v4, v[94:97], s[4:5] offset:256
	s_nop 1
	v_or_b32_e32 v4, 16, v10
	v_mad_u32_u24 v4, v4, s94, v6
	v_cvt_pk_f16_f32 v150, v150, v151
	v_cvt_pk_f16_f32 v151, v152, v153
	v_cvt_pk_f16_f32 v152, v134, v135
	v_cvt_pk_f16_f32 v153, v136, v137
	v_cvt_pk_f16_f32 v86, v86, v87
	v_cvt_pk_f16_f32 v87, v88, v89
	v_cvt_pk_f16_f32 v88, v70, v71
	v_cvt_pk_f16_f32 v89, v72, v73
	v_permlane32_swap_b32_e32 v150, v152
	v_permlane32_swap_b32_e32 v151, v153
	v_permlane32_swap_b32_e32 v86, v88
	v_permlane32_swap_b32_e32 v87, v89
	v_permlane16_swap_b32_e32 v150, v152
	v_permlane16_swap_b32_e32 v151, v153
	v_permlane16_swap_b32_e32 v86, v88
	v_permlane16_swap_b32_e32 v87, v89
	s_nop 1
	ds_bpermute_b32 v150, v9, v150
	ds_bpermute_b32 v151, v9, v151
	ds_bpermute_b32 v152, v9, v152
	ds_bpermute_b32 v153, v9, v153
	ds_bpermute_b32 v86, v9, v86
	ds_bpermute_b32 v87, v9, v87
	ds_bpermute_b32 v88, v9, v88
	ds_bpermute_b32 v89, v9, v89
	s_waitcnt lgkmcnt(0)
	global_store_dwordx4 v4, v[150:153], s[4:5]
	global_store_dwordx4 v4, v[86:89], s[4:5] offset:256
	s_nop 1
	v_or_b32_e32 v4, 32, v10
	v_mad_u32_u24 v4, v4, s94, v6
	v_cvt_pk_f16_f32 v154, v154, v155
	v_cvt_pk_f16_f32 v155, v156, v157
	v_cvt_pk_f16_f32 v156, v138, v139
	v_cvt_pk_f16_f32 v157, v140, v141
	v_cvt_pk_f16_f32 v90, v90, v91
	v_cvt_pk_f16_f32 v91, v92, v93
	v_cvt_pk_f16_f32 v92, v74, v75
	v_cvt_pk_f16_f32 v93, v76, v77
	v_permlane32_swap_b32_e32 v154, v156
	v_permlane32_swap_b32_e32 v155, v157
	v_permlane32_swap_b32_e32 v90, v92
	v_permlane32_swap_b32_e32 v91, v93
	v_permlane16_swap_b32_e32 v154, v156
	v_permlane16_swap_b32_e32 v155, v157
	v_permlane16_swap_b32_e32 v90, v92
	v_permlane16_swap_b32_e32 v91, v93
	s_nop 1
	ds_bpermute_b32 v154, v9, v154
	ds_bpermute_b32 v155, v9, v155
	ds_bpermute_b32 v156, v9, v156
	ds_bpermute_b32 v157, v9, v157
	ds_bpermute_b32 v90, v9, v90
	ds_bpermute_b32 v91, v9, v91
	ds_bpermute_b32 v92, v9, v92
	ds_bpermute_b32 v93, v9, v93
	s_waitcnt lgkmcnt(0)
	global_store_dwordx4 v4, v[154:157], s[4:5]
	global_store_dwordx4 v4, v[90:93], s[4:5] offset:256
	s_nop 1
	v_or_b32_e32 v4, 48, v10
	v_mad_u32_u24 v4, v4, s94, v6
	v_cvt_pk_f16_f32 v146, v146, v147
	v_cvt_pk_f16_f32 v147, v148, v149
	v_cvt_pk_f16_f32 v148, v130, v131
	v_cvt_pk_f16_f32 v149, v132, v133
	v_cvt_pk_f16_f32 v82, v82, v83
	v_cvt_pk_f16_f32 v83, v84, v85
	v_cvt_pk_f16_f32 v84, v66, v67
	v_cvt_pk_f16_f32 v85, v68, v69
	v_permlane32_swap_b32_e32 v146, v148
	v_permlane32_swap_b32_e32 v147, v149
	v_permlane32_swap_b32_e32 v82, v84
	v_permlane32_swap_b32_e32 v83, v85
	v_permlane16_swap_b32_e32 v146, v148
	v_permlane16_swap_b32_e32 v147, v149
	v_permlane16_swap_b32_e32 v82, v84
	v_permlane16_swap_b32_e32 v83, v85
	s_nop 1
	ds_bpermute_b32 v146, v9, v146
	ds_bpermute_b32 v147, v9, v147
	ds_bpermute_b32 v148, v9, v148
	ds_bpermute_b32 v149, v9, v149
	ds_bpermute_b32 v82, v9, v82
	ds_bpermute_b32 v83, v9, v83
	ds_bpermute_b32 v84, v9, v84
	ds_bpermute_b32 v85, v9, v85
	s_waitcnt lgkmcnt(0)
	global_store_dwordx4 v4, v[146:149], s[4:5]
	global_store_dwordx4 v4, v[82:85], s[4:5] offset:256
	s_nop 1
	v_add_u32_e32 v4, 0x80, v10
	v_mad_u32_u24 v4, v4, s94, v6
	v_cvt_pk_f16_f32 v126, v126, v127
	v_cvt_pk_f16_f32 v127, v128, v129
	v_cvt_pk_f16_f32 v128, v110, v111
	v_cvt_pk_f16_f32 v129, v112, v113
	v_cvt_pk_f16_f32 v62, v62, v63
	v_cvt_pk_f16_f32 v63, v64, v65
	v_cvt_pk_f16_f32 v64, v46, v47
	v_cvt_pk_f16_f32 v65, v48, v49
	v_permlane32_swap_b32_e32 v126, v128
	v_permlane32_swap_b32_e32 v127, v129
	v_permlane32_swap_b32_e32 v62, v64
	v_permlane32_swap_b32_e32 v63, v65
	v_permlane16_swap_b32_e32 v126, v128
	v_permlane16_swap_b32_e32 v127, v129
	v_permlane16_swap_b32_e32 v62, v64
	v_permlane16_swap_b32_e32 v63, v65
	s_nop 1
	ds_bpermute_b32 v126, v9, v126
	ds_bpermute_b32 v127, v9, v127
	ds_bpermute_b32 v128, v9, v128
	ds_bpermute_b32 v129, v9, v129
	ds_bpermute_b32 v62, v9, v62
	ds_bpermute_b32 v63, v9, v63
	ds_bpermute_b32 v64, v9, v64
	ds_bpermute_b32 v65, v9, v65
	s_waitcnt lgkmcnt(0)
	global_store_dwordx4 v4, v[126:129], s[4:5]
	global_store_dwordx4 v4, v[62:65], s[4:5] offset:256
	s_nop 1
	v_add_u32_e32 v4, 0x90, v10
	v_mad_u32_u24 v4, v4, s94, v6
	v_cvt_pk_f16_f32 v118, v118, v119
	v_cvt_pk_f16_f32 v119, v120, v121
	v_cvt_pk_f16_f32 v120, v102, v103
	v_cvt_pk_f16_f32 v121, v104, v105
	v_cvt_pk_f16_f32 v54, v54, v55
	v_cvt_pk_f16_f32 v55, v56, v57
	v_cvt_pk_f16_f32 v56, v38, v39
	v_cvt_pk_f16_f32 v57, v40, v41
	v_permlane32_swap_b32_e32 v118, v120
	v_permlane32_swap_b32_e32 v119, v121
	v_permlane32_swap_b32_e32 v54, v56
	v_permlane32_swap_b32_e32 v55, v57
	v_permlane16_swap_b32_e32 v118, v120
	v_permlane16_swap_b32_e32 v119, v121
	v_permlane16_swap_b32_e32 v54, v56
	v_permlane16_swap_b32_e32 v55, v57
	s_nop 1
	ds_bpermute_b32 v118, v9, v118
	ds_bpermute_b32 v119, v9, v119
	ds_bpermute_b32 v120, v9, v120
	ds_bpermute_b32 v121, v9, v121
	ds_bpermute_b32 v54, v9, v54
	ds_bpermute_b32 v55, v9, v55
	ds_bpermute_b32 v56, v9, v56
	ds_bpermute_b32 v57, v9, v57
	s_waitcnt lgkmcnt(0)
	global_store_dwordx4 v4, v[118:121], s[4:5]
	global_store_dwordx4 v4, v[54:57], s[4:5] offset:256
	s_nop 1
	v_add_u32_e32 v4, 0xa0, v10
	v_mad_u32_u24 v4, v4, s94, v6
	v_cvt_pk_f16_f32 v122, v122, v123
	v_cvt_pk_f16_f32 v123, v124, v125
	v_cvt_pk_f16_f32 v124, v106, v107
	v_cvt_pk_f16_f32 v125, v108, v109
	v_cvt_pk_f16_f32 v58, v58, v59
	v_cvt_pk_f16_f32 v59, v60, v61
	v_cvt_pk_f16_f32 v60, v42, v43
	v_cvt_pk_f16_f32 v61, v44, v45
	v_permlane32_swap_b32_e32 v122, v124
	v_permlane32_swap_b32_e32 v123, v125
	v_permlane32_swap_b32_e32 v58, v60
	v_permlane32_swap_b32_e32 v59, v61
	v_permlane16_swap_b32_e32 v122, v124
	v_permlane16_swap_b32_e32 v123, v125
	v_permlane16_swap_b32_e32 v58, v60
	v_permlane16_swap_b32_e32 v59, v61
	s_nop 1
	ds_bpermute_b32 v122, v9, v122
	ds_bpermute_b32 v123, v9, v123
	ds_bpermute_b32 v124, v9, v124
	ds_bpermute_b32 v125, v9, v125
	ds_bpermute_b32 v58, v9, v58
	ds_bpermute_b32 v59, v9, v59
	ds_bpermute_b32 v60, v9, v60
	ds_bpermute_b32 v61, v9, v61
	s_waitcnt lgkmcnt(0)
	global_store_dwordx4 v4, v[122:125], s[4:5]
	global_store_dwordx4 v4, v[58:61], s[4:5] offset:256
	s_nop 1
	v_add_u32_e32 v4, 0xb0, v10
	v_mad_u32_u24 v4, v4, s94, v6
	v_cvt_pk_f16_f32 v114, v114, v115
	v_cvt_pk_f16_f32 v115, v116, v117
	v_cvt_pk_f16_f32 v116, v98, v99
	v_cvt_pk_f16_f32 v117, v100, v101
	v_cvt_pk_f16_f32 v50, v50, v51
	v_cvt_pk_f16_f32 v51, v52, v53
	v_cvt_pk_f16_f32 v52, v34, v35
	v_cvt_pk_f16_f32 v53, v36, v37
	v_permlane32_swap_b32_e32 v114, v116
	v_permlane32_swap_b32_e32 v115, v117
	v_permlane32_swap_b32_e32 v50, v52
	v_permlane32_swap_b32_e32 v51, v53
	v_permlane16_swap_b32_e32 v114, v116
	v_permlane16_swap_b32_e32 v115, v117
	v_permlane16_swap_b32_e32 v50, v52
	v_permlane16_swap_b32_e32 v51, v53
	s_nop 1
	ds_bpermute_b32 v114, v9, v114
	ds_bpermute_b32 v115, v9, v115
	ds_bpermute_b32 v116, v9, v116
	ds_bpermute_b32 v117, v9, v117
	ds_bpermute_b32 v50, v9, v50
	ds_bpermute_b32 v51, v9, v51
	ds_bpermute_b32 v52, v9, v52
	ds_bpermute_b32 v53, v9, v53
	s_waitcnt lgkmcnt(0)
	global_store_dwordx4 v4, v[114:117], s[4:5]
	global_store_dwordx4 v4, v[50:53], s[4:5] offset:256
	s_nop 1
	s_mov_b64 s[4:5], 0
